# P8 HID stores with sc0 sc1 cache policy (write-through)
# speedup vs baseline: 1.0047x; 1.0047x over previous
.LBB0_877:
	s_cmp_eq_u32 s100, 0
	s_cbranch_scc1 .Ldhs8_idle
	s_cmp_lt_i32 s61, 6
	s_cbranch_scc0 .Ldhs8_hi
	s_cmp_lt_i32 s61, 2
	s_cbranch_scc0 .Ldhs8_q1
	s_cmp_lt_i32 s61, 0
	s_cbranch_scc0 .Ldhs8_g9
	global_store_dwordx4 v255, v[226:229], s[16:17] sc0 sc1
	s_branch .Ldhs8_done
.Ldhs8_g9:
	global_store_dwordx4 v255, v[230:233], s[18:19] sc0 sc1
	s_branch .Ldhs8_done
.Ldhs8_q1:
	s_cmp_lt_i32 s61, 4
	s_cbranch_scc0 .Ldhs8_g11
	global_store_dwordx4 v255, v[234:237], s[16:17] offset:1024 sc0 sc1
	s_branch .Ldhs8_done
.Ldhs8_g11:
	global_store_dwordx4 v255, v[238:241], s[18:19] offset:1024 sc0 sc1
	s_branch .Ldhs8_done
.Ldhs8_hi:
	s_cmp_lt_i32 s61, 10
	s_cbranch_scc0 .Ldhs8_q3
	s_cmp_lt_i32 s61, 8
	s_cbranch_scc0 .Ldhs8_g13
	global_store_dwordx4 v255, v[242:245], s[16:17] offset:2048 sc0 sc1
	s_branch .Ldhs8_done
.Ldhs8_g13:
	global_store_dwordx4 v255, v[246:249], s[18:19] offset:2048 sc0 sc1
	s_branch .Ldhs8_done
.Ldhs8_q3:
	s_cmp_lt_i32 s61, 12
	s_cbranch_scc0 .Ldhs8_g15
	global_store_dwordx4 v255, v[250:253], s[16:17] offset:3072 sc0 sc1
	s_branch .Ldhs8_done
.Ldhs8_g15:
	global_store_dwordx4 v255, v[140:143], s[18:19] offset:3072 sc0 sc1
	s_branch .Ldhs8_done

.LBB0_880:
	v_lshl_add_u32 v150, s34, 8, v144
	v_lshl_or_b32 v152, s56, 8, v146
	v_ashrrev_i32_e32 v151, 31, v150
	v_max_f32_e32 v124, 0, v124
	v_max_f32_e32 v120, 0, v120
	v_max_f32_e32 v125, 0, v125
	v_max_f32_e32 v121, 0, v121
	v_max_f32_e32 v126, 0, v126
	v_max_f32_e32 v127, 0, v127
	v_ashrrev_i32_e32 v153, 31, v152
	v_lshlrev_b64 v[154:155], 6, v[150:151]
	v_pk_mul_f32 v[124:125], v[124:125], v[124:125]
	v_pk_mul_f32 v[120:121], v[120:121], v[120:121]
	v_max_f32_e32 v122, 0, v122
	v_max_f32_e32 v123, 0, v123
	v_pk_mul_f32 v[126:127], v[126:127], v[126:127]
	v_pk_mul_f32 v[156:157], v[122:123], v[122:123]
	v_cvt_pk_bf16_f32 v122, v124, v125
	v_cvt_pk_bf16_f32 v123, v126, v127
	v_cvt_pk_bf16_f32 v124, v120, v121
	v_lshl_add_u64 v[120:121], s[78:79], 0, v[154:155]
	v_and_b32_e32 v126, 0xfe0, v152
	v_and_b32_e32 v127, 31, v152
	v_lshlrev_b32_e32 v126, 16, v126
	v_lshl_or_b32 v126, v127, 1, v126
	v_add_u32_e32 v255, v154, v126
	v_mov_b32_e32 v127, 0
	v_cvt_pk_bf16_f32 v125, v156, v157
	v_lshl_add_u64 v[120:121], v[120:121], 0, v[126:127]
	v_max_f32_e32 v112, 0, v112
	v_max_f32_e32 v113, 0, v113
	global_store_dwordx4 v[120:121], v[122:125], off sc0 sc1
	s_nop 1
	v_pk_mul_f32 v[122:123], v[112:113], v[112:113]
	v_max_f32_e32 v114, 0, v114
	v_max_f32_e32 v116, 0, v116
	v_max_f32_e32 v117, 0, v117
	v_max_f32_e32 v112, 0, v118
	v_max_f32_e32 v113, 0, v119
	v_max_f32_e32 v115, 0, v115
	v_pk_mul_f32 v[116:117], v[116:117], v[116:117]
	v_pk_mul_f32 v[118:119], v[112:113], v[112:113]
	v_pk_mul_f32 v[124:125], v[114:115], v[114:115]
	v_cvt_pk_bf16_f32 v112, v116, v117
	v_cvt_pk_bf16_f32 v113, v118, v119
	v_cvt_pk_bf16_f32 v114, v122, v123
	v_cvt_pk_bf16_f32 v115, v124, v125
	v_max_f32_e32 v104, 0, v104
	v_max_f32_e32 v105, 0, v105
	v_lshl_add_u64 v[200:201], v[120:121], 0, s[98:99]
	global_store_dwordx4 v[200:201], v[112:115], off sc0 sc1
	s_nop 1
	v_or_b32_e32 v112, 16, v150
	v_pk_mul_f32 v[114:115], v[104:105], v[104:105]
	v_ashrrev_i32_e32 v113, 31, v112
	v_max_f32_e32 v108, 0, v108
	v_max_f32_e32 v109, 0, v109
	v_max_f32_e32 v106, 0, v106
	v_lshlrev_b64 v[112:113], 6, v[112:113]
	v_pk_mul_f32 v[108:109], v[108:109], v[108:109]
	v_max_f32_e32 v104, 0, v110
	v_max_f32_e32 v105, 0, v111
	v_max_f32_e32 v107, 0, v107
	v_pk_mul_f32 v[110:111], v[104:105], v[104:105]
	v_pk_mul_f32 v[116:117], v[106:107], v[106:107]
	v_cvt_pk_bf16_f32 v104, v108, v109
	v_lshl_add_u64 v[108:109], s[78:79], 0, v[112:113]
	v_cvt_pk_bf16_f32 v105, v110, v111
	v_cvt_pk_bf16_f32 v106, v114, v115
	v_cvt_pk_bf16_f32 v107, v116, v117
	v_lshl_add_u64 v[108:109], v[108:109], 0, v[126:127]
	v_max_f32_e32 v96, 0, v96
	v_max_f32_e32 v97, 0, v97
	global_store_dwordx4 v[108:109], v[104:107], off sc0 sc1
	s_nop 1
	v_pk_mul_f32 v[104:105], v[96:97], v[96:97]
	v_max_f32_e32 v98, 0, v98
	v_max_f32_e32 v100, 0, v100
	v_max_f32_e32 v101, 0, v101
	v_max_f32_e32 v96, 0, v102
	v_max_f32_e32 v97, 0, v103
	v_max_f32_e32 v99, 0, v99
	v_pk_mul_f32 v[100:101], v[100:101], v[100:101]
	v_pk_mul_f32 v[102:103], v[96:97], v[96:97]
	v_pk_mul_f32 v[106:107], v[98:99], v[98:99]
	v_cvt_pk_bf16_f32 v96, v100, v101
	v_cvt_pk_bf16_f32 v97, v102, v103
	v_cvt_pk_bf16_f32 v98, v104, v105
	v_cvt_pk_bf16_f32 v99, v106, v107
	v_max_f32_e32 v88, 0, v88
	v_max_f32_e32 v89, 0, v89
	v_lshl_add_u64 v[202:203], v[108:109], 0, s[98:99]
	global_store_dwordx4 v[202:203], v[96:99], off sc0 sc1
	s_nop 1
	v_or_b32_e32 v96, 32, v150
	v_pk_mul_f32 v[98:99], v[88:89], v[88:89]
	v_ashrrev_i32_e32 v97, 31, v96
	v_max_f32_e32 v92, 0, v92
	v_max_f32_e32 v93, 0, v93
	v_max_f32_e32 v90, 0, v90
	v_lshlrev_b64 v[96:97], 6, v[96:97]
	v_pk_mul_f32 v[92:93], v[92:93], v[92:93]
	v_max_f32_e32 v88, 0, v94
	v_max_f32_e32 v89, 0, v95
	v_max_f32_e32 v91, 0, v91
	v_pk_mul_f32 v[94:95], v[88:89], v[88:89]
	v_pk_mul_f32 v[100:101], v[90:91], v[90:91]
	v_cvt_pk_bf16_f32 v88, v92, v93
	v_lshl_add_u64 v[92:93], s[78:79], 0, v[96:97]
	v_cvt_pk_bf16_f32 v89, v94, v95
	v_cvt_pk_bf16_f32 v90, v98, v99
	v_cvt_pk_bf16_f32 v91, v100, v101
	v_lshl_add_u64 v[92:93], v[92:93], 0, v[126:127]
	v_max_f32_e32 v80, 0, v80
	v_max_f32_e32 v81, 0, v81
	global_store_dwordx4 v[92:93], v[88:91], off sc0 sc1
	s_nop 1
	v_pk_mul_f32 v[88:89], v[80:81], v[80:81]
	v_max_f32_e32 v82, 0, v82
	v_max_f32_e32 v84, 0, v84
	v_max_f32_e32 v85, 0, v85
	v_max_f32_e32 v80, 0, v86
	v_max_f32_e32 v81, 0, v87
	v_max_f32_e32 v83, 0, v83
	v_pk_mul_f32 v[84:85], v[84:85], v[84:85]
	v_pk_mul_f32 v[86:87], v[80:81], v[80:81]
	v_pk_mul_f32 v[90:91], v[82:83], v[82:83]
	v_cvt_pk_bf16_f32 v80, v84, v85
	v_cvt_pk_bf16_f32 v81, v86, v87
	v_cvt_pk_bf16_f32 v82, v88, v89
	v_cvt_pk_bf16_f32 v83, v90, v91
	v_max_f32_e32 v72, 0, v72
	v_max_f32_e32 v73, 0, v73
	v_lshl_add_u64 v[204:205], v[92:93], 0, s[98:99]
	global_store_dwordx4 v[204:205], v[80:83], off sc0 sc1
	s_nop 1
	v_or_b32_e32 v80, 48, v150
	v_pk_mul_f32 v[82:83], v[72:73], v[72:73]
	v_ashrrev_i32_e32 v81, 31, v80
	v_max_f32_e32 v76, 0, v76
	v_max_f32_e32 v77, 0, v77
	v_max_f32_e32 v74, 0, v74
	v_lshlrev_b64 v[80:81], 6, v[80:81]
	v_pk_mul_f32 v[76:77], v[76:77], v[76:77]
	v_max_f32_e32 v72, 0, v78
	v_max_f32_e32 v73, 0, v79
	v_max_f32_e32 v75, 0, v75
	v_pk_mul_f32 v[78:79], v[72:73], v[72:73]
	v_pk_mul_f32 v[84:85], v[74:75], v[74:75]
	v_cvt_pk_bf16_f32 v72, v76, v77
	v_lshl_add_u64 v[76:77], s[78:79], 0, v[80:81]
	v_cvt_pk_bf16_f32 v73, v78, v79
	v_cvt_pk_bf16_f32 v74, v82, v83
	v_cvt_pk_bf16_f32 v75, v84, v85
	v_lshl_add_u64 v[76:77], v[76:77], 0, v[126:127]
	v_max_f32_e32 v64, 0, v64
	v_max_f32_e32 v65, 0, v65
	global_store_dwordx4 v[76:77], v[72:75], off sc0 sc1
	s_nop 1
	v_pk_mul_f32 v[72:73], v[64:65], v[64:65]
	v_max_f32_e32 v66, 0, v66
	v_max_f32_e32 v68, 0, v68
	v_max_f32_e32 v69, 0, v69
	v_max_f32_e32 v64, 0, v70
	v_max_f32_e32 v65, 0, v71
	v_max_f32_e32 v67, 0, v67
	v_pk_mul_f32 v[68:69], v[68:69], v[68:69]
	v_pk_mul_f32 v[70:71], v[64:65], v[64:65]
	v_pk_mul_f32 v[74:75], v[66:67], v[66:67]
	v_cvt_pk_bf16_f32 v64, v68, v69
	v_cvt_pk_bf16_f32 v65, v70, v71
	v_cvt_pk_bf16_f32 v66, v72, v73
	v_cvt_pk_bf16_f32 v67, v74, v75
	v_max_f32_e32 v56, 0, v56
	v_max_f32_e32 v57, 0, v57
	v_lshl_add_u64 v[206:207], v[76:77], 0, s[98:99]
	global_store_dwordx4 v[206:207], v[64:67], off sc0 sc1
	s_nop 1
	v_pk_mul_f32 v[64:65], v[56:57], v[56:57]
	v_max_f32_e32 v58, 0, v58
	v_max_f32_e32 v56, 0, v62
	v_max_f32_e32 v57, 0, v63
	v_max_f32_e32 v60, 0, v60
	v_max_f32_e32 v61, 0, v61
	v_max_f32_e32 v59, 0, v59
	v_pk_mul_f32 v[62:63], v[56:57], v[56:57]
	v_pk_mul_f32 v[60:61], v[60:61], v[60:61]
	v_pk_mul_f32 v[66:67], v[58:59], v[58:59]
	v_cvt_pk_bf16_f32 v227, v62, v63
	v_cvt_pk_bf16_f32 v226, v60, v61
	v_cvt_pk_bf16_f32 v228, v64, v65
	v_cvt_pk_bf16_f32 v229, v66, v67
	v_max_f32_e32 v48, 0, v48
	v_max_f32_e32 v49, 0, v49
	v_pk_mul_f32 v[56:57], v[48:49], v[48:49]
	v_max_f32_e32 v50, 0, v50
	v_max_f32_e32 v52, 0, v52
	v_max_f32_e32 v53, 0, v53
	v_max_f32_e32 v48, 0, v54
	v_max_f32_e32 v49, 0, v55
	v_max_f32_e32 v51, 0, v51
	v_pk_mul_f32 v[52:53], v[52:53], v[52:53]
	v_pk_mul_f32 v[54:55], v[48:49], v[48:49]
	v_pk_mul_f32 v[58:59], v[50:51], v[50:51]
	v_cvt_pk_bf16_f32 v230, v52, v53
	v_cvt_pk_bf16_f32 v231, v54, v55
	v_cvt_pk_bf16_f32 v232, v56, v57
	v_cvt_pk_bf16_f32 v233, v58, v59
	v_max_f32_e32 v40, 0, v40
	v_max_f32_e32 v41, 0, v41
	v_pk_mul_f32 v[48:49], v[40:41], v[40:41]
	v_max_f32_e32 v42, 0, v42
	v_max_f32_e32 v40, 0, v46
	v_max_f32_e32 v41, 0, v47
	v_max_f32_e32 v44, 0, v44
	v_max_f32_e32 v45, 0, v45
	v_max_f32_e32 v43, 0, v43
	v_pk_mul_f32 v[46:47], v[40:41], v[40:41]
	v_pk_mul_f32 v[44:45], v[44:45], v[44:45]
	v_pk_mul_f32 v[50:51], v[42:43], v[42:43]
	v_cvt_pk_bf16_f32 v235, v46, v47
	v_cvt_pk_bf16_f32 v234, v44, v45
	v_cvt_pk_bf16_f32 v236, v48, v49
	v_cvt_pk_bf16_f32 v237, v50, v51
	v_max_f32_e32 v32, 0, v32
	v_max_f32_e32 v33, 0, v33
	v_pk_mul_f32 v[40:41], v[32:33], v[32:33]
	v_max_f32_e32 v34, 0, v34
	v_max_f32_e32 v36, 0, v36
	v_max_f32_e32 v37, 0, v37
	v_max_f32_e32 v32, 0, v38
	v_max_f32_e32 v33, 0, v39
	v_max_f32_e32 v35, 0, v35
	v_pk_mul_f32 v[36:37], v[36:37], v[36:37]
	v_pk_mul_f32 v[38:39], v[32:33], v[32:33]
	v_pk_mul_f32 v[42:43], v[34:35], v[34:35]
	v_cvt_pk_bf16_f32 v238, v36, v37
	v_cvt_pk_bf16_f32 v239, v38, v39
	v_cvt_pk_bf16_f32 v240, v40, v41
	v_cvt_pk_bf16_f32 v241, v42, v43
	v_max_f32_e32 v24, 0, v24
	v_max_f32_e32 v25, 0, v25
	v_pk_mul_f32 v[32:33], v[24:25], v[24:25]
	v_max_f32_e32 v26, 0, v26
	v_max_f32_e32 v24, 0, v30
	v_max_f32_e32 v25, 0, v31
	v_max_f32_e32 v28, 0, v28
	v_max_f32_e32 v29, 0, v29
	v_max_f32_e32 v27, 0, v27
	v_pk_mul_f32 v[30:31], v[24:25], v[24:25]
	v_pk_mul_f32 v[28:29], v[28:29], v[28:29]
	v_pk_mul_f32 v[34:35], v[26:27], v[26:27]
	v_cvt_pk_bf16_f32 v243, v30, v31
	v_cvt_pk_bf16_f32 v242, v28, v29
	v_cvt_pk_bf16_f32 v244, v32, v33
	v_cvt_pk_bf16_f32 v245, v34, v35
	v_max_f32_e32 v16, 0, v16
	v_max_f32_e32 v17, 0, v17
	v_pk_mul_f32 v[24:25], v[16:17], v[16:17]
	v_max_f32_e32 v18, 0, v18
	v_max_f32_e32 v20, 0, v20
	v_max_f32_e32 v21, 0, v21
	v_max_f32_e32 v16, 0, v22
	v_max_f32_e32 v17, 0, v23
	v_max_f32_e32 v19, 0, v19
	v_pk_mul_f32 v[20:21], v[20:21], v[20:21]
	v_pk_mul_f32 v[22:23], v[16:17], v[16:17]
	v_pk_mul_f32 v[26:27], v[18:19], v[18:19]
	v_cvt_pk_bf16_f32 v246, v20, v21
	v_cvt_pk_bf16_f32 v247, v22, v23
	v_cvt_pk_bf16_f32 v248, v24, v25
	v_cvt_pk_bf16_f32 v249, v26, v27
	v_max_f32_e32 v8, 0, v8
	v_max_f32_e32 v9, 0, v9
	v_pk_mul_f32 v[16:17], v[8:9], v[8:9]
	v_max_f32_e32 v10, 0, v10
	v_max_f32_e32 v8, 0, v14
	v_max_f32_e32 v9, 0, v15
	v_max_f32_e32 v12, 0, v12
	v_max_f32_e32 v13, 0, v13
	v_max_f32_e32 v11, 0, v11
	v_pk_mul_f32 v[14:15], v[8:9], v[8:9]
	v_pk_mul_f32 v[12:13], v[12:13], v[12:13]
	v_pk_mul_f32 v[18:19], v[10:11], v[10:11]
	v_cvt_pk_bf16_f32 v251, v14, v15
	v_cvt_pk_bf16_f32 v250, v12, v13
	v_cvt_pk_bf16_f32 v252, v16, v17
	v_cvt_pk_bf16_f32 v253, v18, v19
	v_max_f32_e32 v0, 0, v0
	v_max_f32_e32 v1, 0, v1
	v_pk_mul_f32 v[8:9], v[0:1], v[0:1]
	v_max_f32_e32 v2, 0, v2
	v_max_f32_e32 v4, 0, v4
	v_max_f32_e32 v5, 0, v5
	v_max_f32_e32 v0, 0, v6
	v_max_f32_e32 v1, 0, v7
	v_max_f32_e32 v3, 0, v3
	v_pk_mul_f32 v[4:5], v[4:5], v[4:5]
	v_pk_mul_f32 v[6:7], v[0:1], v[0:1]
	v_pk_mul_f32 v[10:11], v[2:3], v[2:3]
	v_cvt_pk_bf16_f32 v140, v4, v5
	v_cvt_pk_bf16_f32 v141, v6, v7
	v_cvt_pk_bf16_f32 v142, v8, v9
	v_cvt_pk_bf16_f32 v143, v10, v11
	s_andn2_b64 vcc, exec, s[4:5]
	s_mov_b64 s[4:5], -1
	s_mov_b32 s100, 1
	s_cbranch_vccnz .LBB0_869
	s_andn2_b64 vcc, exec, s[6:7]
	s_cbranch_vccnz .LBB0_868
	s_barrier
	s_branch .LBB0_868
.LBB0_883:
	global_store_dwordx4 v255, v[226:229], s[16:17] sc0 sc1
	global_store_dwordx4 v255, v[230:233], s[18:19] sc0 sc1
	global_store_dwordx4 v255, v[234:237], s[16:17] offset:1024 sc0 sc1
	global_store_dwordx4 v255, v[238:241], s[18:19] offset:1024 sc0 sc1
	global_store_dwordx4 v255, v[242:245], s[16:17] offset:2048 sc0 sc1
	global_store_dwordx4 v255, v[246:249], s[18:19] offset:2048 sc0 sc1
	global_store_dwordx4 v255, v[250:253], s[16:17] offset:3072 sc0 sc1
	global_store_dwordx4 v255, v[140:143], s[18:19] offset:3072 sc0 sc1
	s_waitcnt vmcnt(0)
	s_barrier
